# v1 + spatial phase U tile via LDS: 16-byte row-major global loads/stores instead of 2-byte ones
# baseline (speedup 1.0000x reference)
; __device__ __forceinline__ void spatial_phase(const Params& P, LAS unsigned char* lds, int layer, int tid, int wave, int lane, int bid, int G) {
;     ...
;     const int hi = lane >> 5, i16 = lane & 15, pb = (wave & 3) * 32, chh = (wave >> 2) * 64;
;     const unsigned la = lb + (unsigned)((8 * hi + (i16 >> 2)) * 320 + (chh + 16 * ((lane >> 4) & 1) + 4 * (i16 & 3)) * 2);
;     const float* W1 = (const float*)(P.ws + WS_W1) + j * 1024;
;     for (int unit = (G % 8 == 0) ? (bid % 8) * (G / 8) + bid / 8 : bid; unit < (T / 128) * 8; unit += G) {
;         const int n = unit >> 3, g = unit & 7;
;         const int q = tid >> 2, part = tid & 3; const size_t tok = (size_t)n * 128 + q;
;         const f32x4 st0 = *(const f32x4*)(stats + tok * 32 + 8 * part), st1 = *(const f32x4*)(stats + tok * 32 + 8 * part + 4);
;         const int c0 = g * 128 + part * 32;
;         u32x4 vv[4];
; #pragma unroll
;         for (int k = 0; k < 4; ++k) vv[k] = *(const u32x4*)(V + tok * D + c0 + 8 * k);
;         const bf16_t* ap = wsp + ((size_t)g * 128 + pb + (lane & 31)) * 128 + 8 * hi;
;         bf16x8 af[8];
; #pragma unroll
;         for (int s = 0; s < 8; ++s) af[s] = *(const bf16x8*)(ap + 16 * s);
;         unsigned short uu[2][16]; float bsv[16], w1v[16], lgv[2], lbv[2];
; #pragma unroll
;         for (int rr = 0; rr < 16; ++rr) { const int p = pb + 8 * (rr >> 2) + 4 * hi + (rr & 3); bsv[rr] = bs[g * 128 + p]; w1v[rr] = W1[g * 128 + p]; }
; #pragma unroll
;         for (int nt = 0; nt < 2; ++nt) { const int c = chh + 32 * nt + (lane & 31); lgv[nt] = lng[g * 128 + c]; lbv[nt] = lnb[g * 128 + c];
; #pragma unroll
;             for (int rr = 0; rr < 16; ++rr) { const int p = pb + 8 * (rr >> 2) + 4 * hi + (rr & 3); uu[nt][rr] = U[((size_t)n * 128 + p) * D + g * 128 + c]; } }
.LBB0_113:
	s_add_u32 s36, s92, 0x17f00000
	s_addc_u32 s37, s93, 0
	s_add_u32 s20, s92, s20
	s_addc_u32 s21, s93, s0
	v_readlane_b32 s0, v254, 2
	s_lshl_b32 s0, s0, 9
	s_and_b32 s0, s0, 0x7ffffc00
	s_lshl_b64 s[22:23], s[0:1], 2
	s_mov_b32 s0, s69
	v_readlane_b32 s64, v252, 5
	v_readlane_b32 s78, v252, 19
	v_readlane_b32 s79, v252, 20
	s_add_u32 s38, s78, s22
	v_readlane_b32 s72, v252, 13
	s_addc_u32 s39, s79, s23
	v_readlane_b32 s73, v252, 14
	s_add_u32 s40, s72, s22
	v_readlane_b32 s74, v252, 15
	s_addc_u32 s41, s73, s23
	v_readlane_b32 s69, v252, 10
	v_readlane_b32 s75, v252, 16
	s_add_u32 s42, s74, s22
	s_mov_b32 s69, s0
	s_addc_u32 s43, s75, s23
	s_lshl_b32 s0, s62, 5
	s_lshl_b32 s24, s62, 4
	v_ashrrev_i32_e32 v6, 5, v0
	s_and_b32 s0, s0, 0x60
	s_andn2_b32 s24, s24, 63
	s_waitcnt lgkmcnt(0)
	v_lshlrev_b32_e32 v2, 3, v6
	v_lshrrev_b32_e32 v1, 2, v0
	v_lshlrev_b32_e32 v4, 2, v0
	s_add_u32 s22, s92, s22
	v_readlane_b32 s66, v252, 7
	v_and_or_b32 v1, v1, 3, v2
	s_movk_i32 s3, 0x140
	v_and_b32_e32 v3, 16, v0
	v_and_b32_e32 v4, 12, v4
	s_addc_u32 s23, s93, s23
	v_and_b32_e32 v7, 3, v246
	v_readlane_b32 s67, v252, 8
	v_mul_lo_u32 v1, v1, s3
	v_or3_b32 v3, v3, v4, s24
	s_add_u32 s66, s22, 0x340000
	s_waitcnt vmcnt(0)
	v_lshlrev_b32_e32 v96, 5, v7
	v_mov_b32_e32 v97, v80
	v_lshl_add_u32 v81, v3, 1, v1
	s_addc_u32 s67, s23, 0
	v_lshl_add_u64 v[4:5], s[92:93], 0, v[96:97]
	s_mov_b64 s[22:23], 0x1df00000
	v_ashrrev_i32_e32 v3, 31, v2
	v_lshl_add_u64 v[98:99], v[4:5], 0, s[22:23]
	v_and_b32_e32 v4, 31, v0
	v_lshl_add_u64 v[0:1], v[2:3], 1, s[20:21]
	s_mov_b64 s[20:21], 0xb800000
	v_lshl_add_u64 v[100:101], v[0:1], 0, s[20:21]
	v_xor_b32_e32 v0, 1, v223
	v_cmp_lt_i32_e32 vcc, v0, v225
	v_ashrrev_i32_e32 v94, 2, v246
	v_lshl_add_u32 v102, v6, 2, s0
	v_cndmask_b32_e32 v0, v223, v0, vcc
	v_lshlrev_b32_e32 v97, 2, v0
	v_xor_b32_e32 v0, 2, v223
	v_cmp_lt_i32_e32 vcc, v0, v225
	v_or_b32_e32 v104, s24, v4
	v_readlane_b32 s20, v254, 15
	v_cndmask_b32_e32 v0, v223, v0, vcc
	v_readlane_b32 s68, v252, 9
	v_lshlrev_b32_e32 v170, 2, v0
	v_mul_lo_u32 v0, v94, s3
	v_lshlrev_b32_e32 v1, 6, v7
	v_ashrrev_i32_e32 v105, 31, v104
	v_or_b32_e32 v106, 1, v102
	v_or_b32_e32 v108, 2, v102
	v_or_b32_e32 v110, 3, v102
	v_add_u32_e32 v112, 8, v102
	v_add_u32_e32 v114, 9, v102
	v_add_u32_e32 v116, 10, v102
	v_add_u32_e32 v118, 11, v102
	v_add_u32_e32 v120, 16, v102
	v_add_u32_e32 v122, 17, v102
	v_add_u32_e32 v124, 18, v102
	v_add_u32_e32 v126, 19, v102
	v_add_u32_e32 v128, 24, v102
	v_add_u32_e32 v130, 25, v102
	v_add_u32_e32 v132, 26, v102
	v_add_u32_e32 v134, 27, v102
	v_readlane_b32 s21, v254, 16
	s_mov_b32 s68, 0xfffff
	v_ashrrev_i32_e32 v95, 31, v94
	v_or_b32_e32 v171, s0, v4
	v_ashrrev_i32_e32 v103, 31, v102
	v_ashrrev_i32_e32 v107, 31, v106
	v_ashrrev_i32_e32 v109, 31, v108
	v_ashrrev_i32_e32 v111, 31, v110
	v_ashrrev_i32_e32 v113, 31, v112
	v_ashrrev_i32_e32 v115, 31, v114
	v_ashrrev_i32_e32 v117, 31, v116
	v_ashrrev_i32_e32 v119, 31, v118
	v_ashrrev_i32_e32 v121, 31, v120
	v_ashrrev_i32_e32 v123, 31, v122
	v_ashrrev_i32_e32 v125, 31, v124
	v_ashrrev_i32_e32 v127, 31, v126
	v_ashrrev_i32_e32 v129, 31, v128
	v_ashrrev_i32_e32 v131, 31, v130
	v_ashrrev_i32_e32 v133, 31, v132
	v_ashrrev_i32_e32 v135, 31, v134
	v_lshrrev_b32_e32 v138, 4, v246
	v_and_b32_e32 v139, 15, v246
	v_lshlrev_b32_e32 v138, 11, v138
	v_lshl_or_b32 v138, v139, 4, v138
	v_mov_b32_e32 v139, 0
	v_lshl_add_u64 v[136:137], v[138:139], 0, s[20:21]
	v_lshlrev_b32_e32 v162, 4, v246
	v_add_u32_e32 v162, 0xa000, v162
	v_lshlrev_b32_e32 v163, 8, v102
	v_lshl_add_u32 v163, v104, 1, v163
	v_add_u32_e32 v163, 0xa000, v163
	s_lshl_b32 s45, s44, 7
	s_lshl_b32 s52, s30, 7
	v_add_u32_e32 v105, v0, v1
	v_readlane_b32 s65, v252, 6
	v_readlane_b32 s70, v252, 11
	v_readlane_b32 s71, v252, 12
	v_readlane_b32 s76, v252, 17
	v_readlane_b32 s77, v252, 18
.LBB0_114:
	s_ashr_i32 s20, s44, 3
	s_ashr_i32 s21, s20, 31
	s_lshl_b64 s[70:71], s[20:21], 7
	v_lshl_add_u64 v[0:1], s[70:71], 0, v[94:95]
	v_lshlrev_b64 v[2:3], 7, v[0:1]
	v_lshl_add_u64 v[2:3], v[98:99], 0, v[2:3]
	global_load_dwordx4 v[16:19], v[2:3], off offset:16
	global_load_dwordx4 v[20:23], v[2:3], off
	s_and_b32 s0, s45, 0x380
	v_or_b32_e32 v2, s0, v96
	v_lshlrev_b64 v[0:1], 11, v[0:1]
	v_lshl_add_u64 v[0:1], s[36:37], 0, v[0:1]
	v_lshlrev_b32_e32 v2, 1, v2
	v_mov_b32_e32 v3, v80
	v_lshl_add_u64 v[8:9], v[0:1], 0, v[2:3]
	global_load_dwordx4 v[0:3], v[8:9], off offset:48
	global_load_dwordx4 v[4:7], v[8:9], off offset:32
	global_load_dwordx4 v[12:15], v[8:9], off offset:16
	global_load_dwordx4 v[24:27], v[8:9], off
	s_lshl_b64 s[22:23], s[70:71], 11
	s_lshl_b32 s20, s0, 1
	s_add_u32 s22, s22, s20
	s_addc_u32 s23, s23, 0
	v_lshl_add_u64 v[138:139], s[22:23], 0, v[136:137]
	s_mov_b64 s[22:23], 0x10000
	v_lshl_add_u64 v[140:141], v[138:139], 0, s[22:23]
	v_lshl_add_u64 v[142:143], v[140:141], 0, s[22:23]
	v_lshl_add_u64 v[144:145], v[142:143], 0, s[22:23]
	global_load_dwordx4 v[146:149], v[138:139], off
	global_load_dwordx4 v[150:153], v[140:141], off
	global_load_dwordx4 v[154:157], v[142:143], off
	global_load_dwordx4 v[158:161], v[144:145], off
	v_or_b32_e32 v8, s0, v171
	v_lshlrev_b32_e32 v8, 8, v8
	v_mov_b32_e32 v9, v80
	v_lshl_add_u64 v[28:29], v[100:101], 0, v[8:9]
	global_load_dwordx4 v[8:11], v[28:29], off
	global_load_dwordx4 v[90:93], v[28:29], off offset:32
	global_load_dwordx4 v[86:89], v[28:29], off offset:64
	global_load_dwordx4 v[82:85], v[28:29], off offset:96
	global_load_dwordx4 v[76:79], v[28:29], off offset:128
	global_load_dwordx4 v[72:75], v[28:29], off offset:160
	global_load_dwordx4 v[68:71], v[28:29], off offset:192
	global_load_dwordx4 v[64:67], v[28:29], off offset:224
	v_add_u32_e32 v28, s0, v102
	v_ashrrev_i32_e32 v29, 31, v28
	v_lshlrev_b64 v[28:29], 2, v[28:29]
	v_lshl_add_u64 v[30:31], s[38:39], 0, v[28:29]
	v_lshl_add_u64 v[28:29], s[66:67], 0, v[28:29]
	global_load_dwordx4 v[56:59], v[30:31], off
	global_load_dwordx4 v[60:63], v[28:29], off
	global_load_dwordx4 v[48:51], v[30:31], off offset:32
	global_load_dwordx4 v[52:55], v[28:29], off offset:32
	global_load_dwordx4 v[40:43], v[30:31], off offset:64
	global_load_dwordx4 v[44:47], v[28:29], off offset:64
	global_load_dwordx4 v[32:35], v[30:31], off offset:96
	global_load_dwordx4 v[36:39], v[28:29], off offset:96
	v_add_u32_e32 v30, s0, v104
	v_ashrrev_i32_e32 v31, 31, v30
	v_lshlrev_b64 v[30:31], 2, v[30:31]
	v_lshl_add_u64 v[172:173], s[40:41], 0, v[30:31]
	v_lshl_add_u64 v[30:31], s[42:43], 0, v[30:31]
	global_load_dword v176, v[172:173], off
	global_load_dword v177, v[30:31], off
	global_load_dword v178, v[172:173], off offset:128
	global_load_dword v179, v[30:31], off offset:128
	s_mov_b32 s0, 0x3a800000
	s_waitcnt vmcnt(29)
; #define LAS __attribute__((address_space(3)))
; #define LAS __attribute__((address_space(3)))
; __device__ __forceinline__ unsigned cvtpk(float lo, float hi) { f32x2_t v = {lo, hi}; bf16x2_t b = __builtin_convertvector(v, bf16x2_t); return __builtin_bit_cast(unsigned, b); }
; __device__ __forceinline__ void spatial_phase(const Params& P, LAS unsigned char* lds, int layer, int tid, int wave, int lane, int bid, int G) {
;     ...
;         const f32x4 st0 = *(const f32x4*)(stats + tok * 32 + 8 * part), st1 = *(const f32x4*)(stats + tok * 32 + 8 * part + 4);
;         const int c0 = g * 128 + part * 32;
;         u32x4 vv[4];
; #pragma unroll
;         for (int k = 0; k < 4; ++k) vv[k] = *(const u32x4*)(V + tok * D + c0 + 8 * k);
;         const bf16_t* ap = wsp + ((size_t)g * 128 + pb + (lane & 31)) * 128 + 8 * hi;
;         bf16x8 af[8];
; #pragma unroll
;         for (int s = 0; s < 8; ++s) af[s] = *(const bf16x8*)(ap + 16 * s);
;         unsigned short uu[2][16]; float bsv[16], w1v[16], lgv[2], lbv[2];
; #pragma unroll
;         for (int rr = 0; rr < 16; ++rr) { const int p = pb + 8 * (rr >> 2) + 4 * hi + (rr & 3); bsv[rr] = bs[g * 128 + p]; w1v[rr] = W1[g * 128 + p]; }
; #pragma unroll
;         for (int nt = 0; nt < 2; ++nt) { const int c = chh + 32 * nt + (lane & 31); lgv[nt] = lng[g * 128 + c]; lbv[nt] = lnb[g * 128 + c];
; #pragma unroll
;             for (int rr = 0; rr < 16; ++rr) { const int p = pb + 8 * (rr >> 2) + 4 * hi + (rr & 3); uu[nt][rr] = U[((size_t)n * 128 + p) * D + g * 128 + c]; } }
;         { float s1 = (st0[0] + st0[2]) + (st1[0] + st1[2]), s2 = (st0[1] + st0[3]) + (st1[1] + st1[3]);
;           s1 += __shfl_xor(s1, 1); s1 += __shfl_xor(s1, 2); s2 += __shfl_xor(s2, 1); s2 += __shfl_xor(s2, 2);
;           const float mean = s1 * (1.0f / D), var = s2 * (1.0f / D) - mean * mean, rstd = __builtin_amdgcn_rsqf(fmaxf(var, 0.f) + EPS);
; #pragma unroll
;           for (int k = 0; k < 4; ++k) { const u32x4 v = vv[k]; u32x4 w;
;               w.x = cvtpk((bflo(v.x) - mean) * rstd, (bfhi(v.x) - mean) * rstd); w.y = cvtpk((bflo(v.y) - mean) * rstd, (bfhi(v.y) - mean) * rstd);
;               w.z = cvtpk((bflo(v.z) - mean) * rstd, (bfhi(v.z) - mean) * rstd); w.w = cvtpk((bflo(v.w) - mean) * rstd, (bfhi(v.w) - mean) * rstd);
;               *(LAS u32x4*)(lds + q * 320 + (part * 32 + 8 * k) * 2) = w; } }
;         __syncthreads();
	v_pk_add_f32 v[16:17], v[16:17], v[18:19]
	s_waitcnt vmcnt(28)
	v_pk_add_f32 v[20:21], v[20:21], v[22:23]
	s_nop 0
	v_pk_add_f32 v[16:17], v[20:21], v[16:17]
	s_nop 1
	ds_bpermute_b32 v18, v97, v16
	ds_bpermute_b32 v19, v97, v17
	s_waitcnt lgkmcnt(0)
	v_pk_add_f32 v[16:17], v[16:17], v[18:19]
	ds_bpermute_b32 v18, v170, v16
	ds_bpermute_b32 v19, v170, v17
	s_waitcnt lgkmcnt(0)
	v_pk_add_f32 v[16:17], v[16:17], v[18:19]
	s_nop 0
	v_pk_mul_f32 v[20:21], v[16:17], s[0:1] op_sel_hi:[1,0]
	s_waitcnt vmcnt(24)
	v_and_b32_e32 v17, 0xffff0000, v24
	v_fma_f32 v16, -v20, v20, v21
	v_max_f32_e32 v16, 0, v16
	v_add_f32_e32 v16, 0x358637bd, v16
	v_rsq_f32_e32 v22, v16
	v_lshlrev_b32_e32 v16, 16, v24
	v_lshlrev_b32_e32 v18, 16, v25
	v_and_b32_e32 v19, 0xffff0000, v25
	v_pk_add_f32 v[16:17], v[16:17], v[20:21] op_sel_hi:[1,0] neg_lo:[0,1] neg_hi:[0,1]
	v_pk_add_f32 v[18:19], v[18:19], v[20:21] op_sel_hi:[1,0] neg_lo:[0,1] neg_hi:[0,1]
	v_pk_mul_f32 v[16:17], v[16:17], v[22:23] op_sel_hi:[1,0]
	v_pk_mul_f32 v[18:19], v[18:19], v[22:23] op_sel_hi:[1,0]
	v_cvt_pk_bf16_f32 v16, v16, v17
	v_cvt_pk_bf16_f32 v17, v18, v19
	v_lshlrev_b32_e32 v18, 16, v26
	v_and_b32_e32 v19, 0xffff0000, v26
	v_lshlrev_b32_e32 v24, 16, v27
	v_and_b32_e32 v25, 0xffff0000, v27
	v_pk_add_f32 v[18:19], v[18:19], v[20:21] op_sel_hi:[1,0] neg_lo:[0,1] neg_hi:[0,1]
	v_pk_add_f32 v[24:25], v[24:25], v[20:21] op_sel_hi:[1,0] neg_lo:[0,1] neg_hi:[0,1]
	v_pk_mul_f32 v[18:19], v[18:19], v[22:23] op_sel_hi:[1,0]
	v_pk_mul_f32 v[24:25], v[24:25], v[22:23] op_sel_hi:[1,0]
	v_cvt_pk_bf16_f32 v18, v18, v19
	v_cvt_pk_bf16_f32 v19, v24, v25
	ds_write_b128 v105, v[16:19]
	v_lshlrev_b32_e32 v16, 16, v12
	v_and_b32_e32 v17, 0xffff0000, v12
	v_pk_add_f32 v[16:17], v[16:17], v[20:21] op_sel_hi:[1,0] neg_lo:[0,1] neg_hi:[0,1]
	s_nop 0
	v_pk_mul_f32 v[16:17], v[16:17], v[22:23] op_sel_hi:[1,0]
	s_nop 0
	v_cvt_pk_bf16_f32 v12, v16, v17
	v_lshlrev_b32_e32 v16, 16, v13
	v_and_b32_e32 v17, 0xffff0000, v13
	v_pk_add_f32 v[16:17], v[16:17], v[20:21] op_sel_hi:[1,0] neg_lo:[0,1] neg_hi:[0,1]
	s_nop 0
	v_pk_mul_f32 v[16:17], v[16:17], v[22:23] op_sel_hi:[1,0]
	s_nop 0
	v_cvt_pk_bf16_f32 v13, v16, v17
	v_lshlrev_b32_e32 v16, 16, v14
	v_and_b32_e32 v17, 0xffff0000, v14
	v_pk_add_f32 v[16:17], v[16:17], v[20:21] op_sel_hi:[1,0] neg_lo:[0,1] neg_hi:[0,1]
	s_nop 0
	v_pk_mul_f32 v[16:17], v[16:17], v[22:23] op_sel_hi:[1,0]
	s_nop 0
	v_cvt_pk_bf16_f32 v14, v16, v17
	v_lshlrev_b32_e32 v16, 16, v15
	v_and_b32_e32 v17, 0xffff0000, v15
	v_pk_add_f32 v[16:17], v[16:17], v[20:21] op_sel_hi:[1,0] neg_lo:[0,1] neg_hi:[0,1]
	s_nop 0
	v_pk_mul_f32 v[16:17], v[16:17], v[22:23] op_sel_hi:[1,0]
	s_nop 0
	v_cvt_pk_bf16_f32 v15, v16, v17
	ds_write_b128 v105, v[12:15] offset:16
	v_lshlrev_b32_e32 v12, 16, v4
	v_and_b32_e32 v13, 0xffff0000, v4
	v_pk_add_f32 v[12:13], v[12:13], v[20:21] op_sel_hi:[1,0] neg_lo:[0,1] neg_hi:[0,1]
	s_nop 0
	v_pk_mul_f32 v[12:13], v[12:13], v[22:23] op_sel_hi:[1,0]
	s_nop 0
	v_cvt_pk_bf16_f32 v4, v12, v13
	v_lshlrev_b32_e32 v12, 16, v5
	v_and_b32_e32 v13, 0xffff0000, v5
	v_pk_add_f32 v[12:13], v[12:13], v[20:21] op_sel_hi:[1,0] neg_lo:[0,1] neg_hi:[0,1]
	s_nop 0
	v_pk_mul_f32 v[12:13], v[12:13], v[22:23] op_sel_hi:[1,0]
	s_nop 0
	v_cvt_pk_bf16_f32 v5, v12, v13
	v_lshlrev_b32_e32 v12, 16, v6
	v_and_b32_e32 v13, 0xffff0000, v6
	v_pk_add_f32 v[12:13], v[12:13], v[20:21] op_sel_hi:[1,0] neg_lo:[0,1] neg_hi:[0,1]
	s_nop 0
	v_pk_mul_f32 v[12:13], v[12:13], v[22:23] op_sel_hi:[1,0]
	s_nop 0
	v_cvt_pk_bf16_f32 v6, v12, v13
	v_lshlrev_b32_e32 v12, 16, v7
	v_and_b32_e32 v13, 0xffff0000, v7
	v_pk_add_f32 v[12:13], v[12:13], v[20:21] op_sel_hi:[1,0] neg_lo:[0,1] neg_hi:[0,1]
	s_nop 0
	v_pk_mul_f32 v[12:13], v[12:13], v[22:23] op_sel_hi:[1,0]
	s_nop 0
	v_cvt_pk_bf16_f32 v7, v12, v13
	ds_write_b128 v105, v[4:7] offset:32
	v_lshlrev_b32_e32 v4, 16, v0
	v_and_b32_e32 v5, 0xffff0000, v0
	v_pk_add_f32 v[4:5], v[4:5], v[20:21] op_sel_hi:[1,0] neg_lo:[0,1] neg_hi:[0,1]
	s_nop 0
	v_pk_mul_f32 v[4:5], v[4:5], v[22:23] op_sel_hi:[1,0]
	s_nop 0
	v_cvt_pk_bf16_f32 v0, v4, v5
	v_lshlrev_b32_e32 v4, 16, v1
	v_and_b32_e32 v5, 0xffff0000, v1
	v_pk_add_f32 v[4:5], v[4:5], v[20:21] op_sel_hi:[1,0] neg_lo:[0,1] neg_hi:[0,1]
	s_nop 0
	v_pk_mul_f32 v[4:5], v[4:5], v[22:23] op_sel_hi:[1,0]
	s_nop 0
	v_cvt_pk_bf16_f32 v1, v4, v5
	v_lshlrev_b32_e32 v4, 16, v2
	v_and_b32_e32 v5, 0xffff0000, v2
	v_pk_add_f32 v[4:5], v[4:5], v[20:21] op_sel_hi:[1,0] neg_lo:[0,1] neg_hi:[0,1]
	s_nop 0
	v_pk_mul_f32 v[4:5], v[4:5], v[22:23] op_sel_hi:[1,0]
	s_nop 0
	v_cvt_pk_bf16_f32 v2, v4, v5
	v_lshlrev_b32_e32 v4, 16, v3
	v_and_b32_e32 v5, 0xffff0000, v3
	v_pk_add_f32 v[4:5], v[4:5], v[20:21] op_sel_hi:[1,0] neg_lo:[0,1] neg_hi:[0,1]
	s_nop 0
	v_pk_mul_f32 v[4:5], v[4:5], v[22:23] op_sel_hi:[1,0]
	s_nop 0
	v_cvt_pk_bf16_f32 v3, v4, v5
	ds_write_b128 v105, v[0:3] offset:48
	s_waitcnt vmcnt(20)
	ds_write_b128 v162, v[146:149]
	ds_write_b128 v162, v[150:153] offset:8192
	ds_write_b128 v162, v[154:157] offset:16384
	ds_write_b128 v162, v[158:161] offset:24576
	s_waitcnt lgkmcnt(0)
	s_barrier
; #define MFMA32(a, b, c) __builtin_amdgcn_mfma_f32_32x32x16_bf16((a), (b), (c), 0, 0, 0)
; #define TRRD2(dst, off) asm volatile("ds_read_b64_tr_b16 %0, %1 offset:%2" : "=&v"(dst) : "v"(la), "i"(off) : "memory")
; __device__ __forceinline__ void spatial_phase(const Params& P, LAS unsigned char* lds, int layer, int tid, int wave, int lane, int bid, int G) {
;     ...
;         for (int nt = 0; nt < 2; ++nt) { const int c = chh + 32 * nt + (lane & 31); lgv[nt] = lng[g * 128 + c]; lbv[nt] = lnb[g * 128 + c];
; #pragma unroll
;             for (int rr = 0; rr < 16; ++rr) { const int p = pb + 8 * (rr >> 2) + 4 * hi + (rr & 3); uu[nt][rr] = U[((size_t)n * 128 + p) * D + g * 128 + c]; } }
;     ...
;         f32x16 acc[2];
; #pragma unroll
;         for (int i = 0; i < 16; ++i) { acc[0][i] = 0.f; acc[1][i] = 0.f; }
; #pragma unroll
;         for (int s = 0; s < 8; ++s) {
;             s16x4 t[4];
;     ...
;             TRRD2(t[0], s * 16 * 320); TRRD2(t[1], s * 16 * 320 + 4 * 320); TRRD2(t[2], s * 16 * 320 + 64); TRRD2(t[3], s * 16 * 320 + 4 * 320 + 64);
;             asm volatile("s_waitcnt lgkmcnt(0)" : "+v"(t[0]), "+v"(t[1]), "+v"(t[2]), "+v"(t[3]) :: "memory");
; #pragma unroll
;             for (int nt = 0; nt < 2; ++nt) { const bf16x8 b = __builtin_shufflevector(t[2 * nt], t[2 * nt + 1], 0, 1, 2, 3, 4, 5, 6, 7); acc[nt] = MFMA32(af[s], b, acc[nt]); }
;         }
	ds_read_b64_tr_b16 v[0:1], v81 offset:0
	ds_read_b64_tr_b16 v[2:3], v81 offset:0x500
	ds_read_b64_tr_b16 v[4:5], v81 offset:64
	ds_read_b64_tr_b16 v[6:7], v81 offset:0x540
	s_nop 0
	s_waitcnt lgkmcnt(0)
	ds_read_b64_tr_b16 v[172:173], v81 offset:0x1400
	ds_read_b64_tr_b16 v[174:175], v81 offset:0x1900
	ds_read_b64_tr_b16 v[182:183], v81 offset:0x1440
	ds_read_b64_tr_b16 v[184:185], v81 offset:0x1940
	s_waitcnt vmcnt(19)
	v_mfma_f32_32x32x16_bf16 v[16:31], v[8:11], v[0:3], 0
	s_waitcnt lgkmcnt(0)
	v_mfma_f32_32x32x16_bf16 v[0:15], v[8:11], v[4:7], 0
	s_waitcnt vmcnt(18)
	v_mfma_f32_32x32x16_bf16 v[16:31], v[90:93], v[172:175], v[16:31]
	v_mfma_f32_32x32x16_bf16 v[0:15], v[90:93], v[182:185], v[0:15]
	ds_read_b64_tr_b16 v[90:91], v81 offset:0x2800
	ds_read_b64_tr_b16 v[92:93], v81 offset:0x2d00
	ds_read_b64_tr_b16 v[172:173], v81 offset:0x2840
	ds_read_b64_tr_b16 v[174:175], v81 offset:0x2d40
	s_nop 0
	s_waitcnt lgkmcnt(0)
	s_waitcnt vmcnt(17)
	v_mfma_f32_32x32x16_bf16 v[16:31], v[86:89], v[90:93], v[16:31]
	v_mfma_f32_32x32x16_bf16 v[0:15], v[86:89], v[172:175], v[0:15]
	ds_read_b64_tr_b16 v[86:87], v81 offset:0x3c00
	ds_read_b64_tr_b16 v[88:89], v81 offset:0x4100
	ds_read_b64_tr_b16 v[90:91], v81 offset:0x3c40
	ds_read_b64_tr_b16 v[92:93], v81 offset:0x4140
	s_nop 0
	s_waitcnt lgkmcnt(0)
	s_waitcnt vmcnt(16)
	v_mfma_f32_32x32x16_bf16 v[16:31], v[82:85], v[86:89], v[16:31]
	v_mfma_f32_32x32x16_bf16 v[0:15], v[82:85], v[90:93], v[0:15]
	ds_read_b64_tr_b16 v[82:83], v81 offset:0x5000
	ds_read_b64_tr_b16 v[84:85], v81 offset:0x5500
	ds_read_b64_tr_b16 v[86:87], v81 offset:0x5040
	ds_read_b64_tr_b16 v[88:89], v81 offset:0x5540
	s_nop 0
	s_waitcnt lgkmcnt(0)
	s_waitcnt vmcnt(15)
	v_mfma_f32_32x32x16_bf16 v[16:31], v[76:79], v[82:85], v[16:31]
	v_mfma_f32_32x32x16_bf16 v[0:15], v[76:79], v[86:89], v[0:15]
	ds_read_b64_tr_b16 v[76:77], v81 offset:0x6400
	ds_read_b64_tr_b16 v[78:79], v81 offset:0x6900
	ds_read_b64_tr_b16 v[82:83], v81 offset:0x6440
	ds_read_b64_tr_b16 v[84:85], v81 offset:0x6940
	s_nop 0
	s_waitcnt lgkmcnt(0)
	s_waitcnt vmcnt(14)
	v_mfma_f32_32x32x16_bf16 v[16:31], v[72:75], v[76:79], v[16:31]
	v_mfma_f32_32x32x16_bf16 v[0:15], v[72:75], v[82:85], v[0:15]
	ds_read_b64_tr_b16 v[72:73], v81 offset:0x7800
	ds_read_b64_tr_b16 v[74:75], v81 offset:0x7d00
	ds_read_b64_tr_b16 v[76:77], v81 offset:0x7840
	ds_read_b64_tr_b16 v[78:79], v81 offset:0x7d40
	s_nop 0
	s_waitcnt lgkmcnt(0)
	s_waitcnt vmcnt(13)
	v_mfma_f32_32x32x16_bf16 v[16:31], v[68:71], v[72:75], v[16:31]
	v_mfma_f32_32x32x16_bf16 v[0:15], v[68:71], v[76:79], v[0:15]
	ds_read_b64_tr_b16 v[68:69], v81 offset:0x8c00
	ds_read_b64_tr_b16 v[70:71], v81 offset:0x9100
	ds_read_b64_tr_b16 v[72:73], v81 offset:0x8c40
	ds_read_b64_tr_b16 v[74:75], v81 offset:0x9140
	s_nop 0
	s_waitcnt lgkmcnt(0)
	s_waitcnt vmcnt(12)
	v_mfma_f32_32x32x16_bf16 v[16:31], v[64:67], v[68:71], v[16:31]
	v_mfma_f32_32x32x16_bf16 v[0:15], v[64:67], v[72:75], v[0:15]
	ds_read_u16 v180, v163
	ds_read_u16 v181, v163 offset:256
	ds_read_u16 v194, v163 offset:512
	ds_read_u16 v195, v163 offset:768
	ds_read_u16 v196, v163 offset:2048
	ds_read_u16 v197, v163 offset:2304
	ds_read_u16 v198, v163 offset:2560
	ds_read_u16 v199, v163 offset:2816
	ds_read_u16 v200, v163 offset:4096
	ds_read_u16 v201, v163 offset:4352
	ds_read_u16 v202, v163 offset:4608
	ds_read_u16 v203, v163 offset:4864
	ds_read_u16 v204, v163 offset:6144
	ds_read_u16 v205, v163 offset:6400
	ds_read_u16 v206, v163 offset:6656
	ds_read_u16 v207, v163 offset:6912
	ds_read_u16 v208, v163 offset:64
	ds_read_u16 v209, v163 offset:320
	ds_read_u16 v210, v163 offset:576
	ds_read_u16 v211, v163 offset:832
	ds_read_u16 v212, v163 offset:2112
	ds_read_u16 v213, v163 offset:2368
	ds_read_u16 v214, v163 offset:2624
	ds_read_u16 v215, v163 offset:2880
	ds_read_u16 v216, v163 offset:4160
	ds_read_u16 v217, v163 offset:4416
	ds_read_u16 v218, v163 offset:4672
	ds_read_u16 v219, v163 offset:4928
	ds_read_u16 v226, v163 offset:6208
	ds_read_u16 v227, v163 offset:6464
	ds_read_u16 v228, v163 offset:6720
	ds_read_u16 v229, v163 offset:6976
	s_waitcnt vmcnt(0)
	s_waitcnt lgkmcnt(0)
; __device__ __forceinline__ unsigned cvtpk(float lo, float hi) { f32x2_t v = {lo, hi}; bf16x2_t b = __builtin_convertvector(v, bf16x2_t); return __builtin_bit_cast(unsigned, b); }
; __device__ __forceinline__ void spatial_phase(const Params& P, LAS unsigned char* lds, int layer, int tid, int wave, int lane, int bid, int G) {
;     ...
; #pragma unroll
;         for (int nt = 0; nt < 2; ++nt)
; #pragma unroll
;             for (int rr = 0; rr < 16; ++rr) {
;                 const int p = pb + 8 * (rr >> 2) + 4 * hi + (rr & 3), c = chh + 32 * nt + (lane & 31);
;                 const float uv = __builtin_bit_cast(float, (unsigned)uu[nt][rr] << 16) * (lgv[nt] * acc[nt][rr] + (lbv[nt] * w1v[rr] + bsv[rr]));
;                 U[((size_t)n * 128 + p) * D + g * 128 + c] = (bf16_t)(cvtpk(uv, 0.f) & 0xffffu);
;             }
;         __syncthreads();
;     }
	v_fma_f32 v64, v60, v177, v56
	v_lshlrev_b32_e32 v180, 16, v180
	v_fmac_f32_e32 v64, v176, v16
	v_mul_f32_e32 v64, v64, v180
	v_cvt_pk_bf16_f32 v64, v64, s0
	ds_write_b16 v163, v64
	v_fma_f32 v65, v61, v177, v57
	v_lshlrev_b32_e32 v181, 16, v181
	v_fmac_f32_e32 v65, v176, v17
	v_mul_f32_e32 v65, v65, v181
	v_cvt_pk_bf16_f32 v65, v65, s0
	ds_write_b16 v163, v65 offset:256
	v_fma_f32 v66, v62, v177, v58
	v_lshlrev_b32_e32 v194, 16, v194
	v_fmac_f32_e32 v66, v176, v18
	v_mul_f32_e32 v66, v66, v194
	v_cvt_pk_bf16_f32 v66, v66, s0
	ds_write_b16 v163, v66 offset:512
	v_fma_f32 v67, v63, v177, v59
	v_lshlrev_b32_e32 v195, 16, v195
	v_fmac_f32_e32 v67, v176, v19
	v_mul_f32_e32 v67, v67, v195
	v_cvt_pk_bf16_f32 v67, v67, s0
	ds_write_b16 v163, v67 offset:768
	v_fma_f32 v68, v52, v177, v48
	v_lshlrev_b32_e32 v196, 16, v196
	v_fmac_f32_e32 v68, v176, v20
	v_mul_f32_e32 v68, v68, v196
	v_cvt_pk_bf16_f32 v68, v68, s0
	ds_write_b16 v163, v68 offset:2048
	v_fma_f32 v69, v53, v177, v49
	v_lshlrev_b32_e32 v197, 16, v197
	v_fmac_f32_e32 v69, v176, v21
	v_mul_f32_e32 v69, v69, v197
	v_cvt_pk_bf16_f32 v69, v69, s0
	ds_write_b16 v163, v69 offset:2304
	v_fma_f32 v70, v54, v177, v50
	v_lshlrev_b32_e32 v198, 16, v198
	v_fmac_f32_e32 v70, v176, v22
	v_mul_f32_e32 v70, v70, v198
	v_cvt_pk_bf16_f32 v70, v70, s0
	ds_write_b16 v163, v70 offset:2560
	v_fma_f32 v71, v55, v177, v51
	v_lshlrev_b32_e32 v199, 16, v199
	v_fmac_f32_e32 v71, v176, v23
	v_mul_f32_e32 v71, v71, v199
	v_cvt_pk_bf16_f32 v71, v71, s0
	ds_write_b16 v163, v71 offset:2816
	v_fma_f32 v64, v44, v177, v40
	v_lshlrev_b32_e32 v200, 16, v200
	v_fmac_f32_e32 v64, v176, v24
	v_mul_f32_e32 v64, v64, v200
	v_cvt_pk_bf16_f32 v64, v64, s0
	ds_write_b16 v163, v64 offset:4096
	v_fma_f32 v65, v45, v177, v41
	v_lshlrev_b32_e32 v201, 16, v201
	v_fmac_f32_e32 v65, v176, v25
	v_mul_f32_e32 v65, v65, v201
	v_cvt_pk_bf16_f32 v65, v65, s0
	ds_write_b16 v163, v65 offset:4352
	v_fma_f32 v66, v46, v177, v42
	v_lshlrev_b32_e32 v202, 16, v202
	v_fmac_f32_e32 v66, v176, v26
	v_mul_f32_e32 v66, v66, v202
	v_cvt_pk_bf16_f32 v66, v66, s0
	ds_write_b16 v163, v66 offset:4608
	v_fma_f32 v67, v47, v177, v43
	v_lshlrev_b32_e32 v203, 16, v203
	v_fmac_f32_e32 v67, v176, v27
	v_mul_f32_e32 v67, v67, v203
	v_cvt_pk_bf16_f32 v67, v67, s0
	ds_write_b16 v163, v67 offset:4864
	v_fma_f32 v68, v36, v177, v32
	v_lshlrev_b32_e32 v204, 16, v204
	v_fmac_f32_e32 v68, v176, v28
	v_mul_f32_e32 v68, v68, v204
	v_cvt_pk_bf16_f32 v68, v68, s0
	ds_write_b16 v163, v68 offset:6144
	v_fma_f32 v69, v37, v177, v33
	v_lshlrev_b32_e32 v205, 16, v205
	v_fmac_f32_e32 v69, v176, v29
	v_mul_f32_e32 v69, v69, v205
	v_cvt_pk_bf16_f32 v69, v69, s0
	ds_write_b16 v163, v69 offset:6400
	v_fma_f32 v70, v38, v177, v34
	v_lshlrev_b32_e32 v206, 16, v206
	v_fmac_f32_e32 v70, v176, v30
	v_mul_f32_e32 v70, v70, v206
	v_cvt_pk_bf16_f32 v70, v70, s0
	ds_write_b16 v163, v70 offset:6656
	v_fma_f32 v71, v39, v177, v35
	v_lshlrev_b32_e32 v207, 16, v207
	v_fmac_f32_e32 v71, v176, v31
	v_mul_f32_e32 v71, v71, v207
	v_cvt_pk_bf16_f32 v71, v71, s0
	ds_write_b16 v163, v71 offset:6912
	v_fma_f32 v64, v60, v179, v56
	v_lshlrev_b32_e32 v208, 16, v208
	v_fmac_f32_e32 v64, v178, v0
	v_mul_f32_e32 v64, v64, v208
	v_cvt_pk_bf16_f32 v64, v64, s0
	ds_write_b16 v163, v64 offset:64
	v_fma_f32 v65, v61, v179, v57
	v_lshlrev_b32_e32 v209, 16, v209
	v_fmac_f32_e32 v65, v178, v1
	v_mul_f32_e32 v65, v65, v209
	v_cvt_pk_bf16_f32 v65, v65, s0
	ds_write_b16 v163, v65 offset:320
	v_fma_f32 v66, v62, v179, v58
	v_lshlrev_b32_e32 v210, 16, v210
	v_fmac_f32_e32 v66, v178, v2
	v_mul_f32_e32 v66, v66, v210
	v_cvt_pk_bf16_f32 v66, v66, s0
	ds_write_b16 v163, v66 offset:576
	v_fma_f32 v67, v63, v179, v59
	v_lshlrev_b32_e32 v211, 16, v211
	v_fmac_f32_e32 v67, v178, v3
	v_mul_f32_e32 v67, v67, v211
	v_cvt_pk_bf16_f32 v67, v67, s0
	ds_write_b16 v163, v67 offset:832
	v_fma_f32 v68, v52, v179, v48
	v_lshlrev_b32_e32 v212, 16, v212
	v_fmac_f32_e32 v68, v178, v4
	v_mul_f32_e32 v68, v68, v212
	v_cvt_pk_bf16_f32 v68, v68, s0
	ds_write_b16 v163, v68 offset:2112
	v_fma_f32 v69, v53, v179, v49
	v_lshlrev_b32_e32 v213, 16, v213
	v_fmac_f32_e32 v69, v178, v5
	v_mul_f32_e32 v69, v69, v213
	v_cvt_pk_bf16_f32 v69, v69, s0
	ds_write_b16 v163, v69 offset:2368
	v_fma_f32 v70, v54, v179, v50
	v_lshlrev_b32_e32 v214, 16, v214
	v_fmac_f32_e32 v70, v178, v6
	v_mul_f32_e32 v70, v70, v214
	v_cvt_pk_bf16_f32 v70, v70, s0
	ds_write_b16 v163, v70 offset:2624
	v_fma_f32 v71, v55, v179, v51
	v_lshlrev_b32_e32 v215, 16, v215
	v_fmac_f32_e32 v71, v178, v7
	v_mul_f32_e32 v71, v71, v215
	v_cvt_pk_bf16_f32 v71, v71, s0
	ds_write_b16 v163, v71 offset:2880
	v_fma_f32 v64, v44, v179, v40
	v_lshlrev_b32_e32 v216, 16, v216
	v_fmac_f32_e32 v64, v178, v8
	v_mul_f32_e32 v64, v64, v216
	v_cvt_pk_bf16_f32 v64, v64, s0
	ds_write_b16 v163, v64 offset:4160
	v_fma_f32 v65, v45, v179, v41
	v_lshlrev_b32_e32 v217, 16, v217
	v_fmac_f32_e32 v65, v178, v9
	v_mul_f32_e32 v65, v65, v217
	v_cvt_pk_bf16_f32 v65, v65, s0
	ds_write_b16 v163, v65 offset:4416
	v_fma_f32 v66, v46, v179, v42
	v_lshlrev_b32_e32 v218, 16, v218
	v_fmac_f32_e32 v66, v178, v10
	v_mul_f32_e32 v66, v66, v218
	v_cvt_pk_bf16_f32 v66, v66, s0
	ds_write_b16 v163, v66 offset:4672
	v_fma_f32 v67, v47, v179, v43
	v_lshlrev_b32_e32 v219, 16, v219
	v_fmac_f32_e32 v67, v178, v11
	v_mul_f32_e32 v67, v67, v219
	v_cvt_pk_bf16_f32 v67, v67, s0
	ds_write_b16 v163, v67 offset:4928
	v_fma_f32 v68, v36, v179, v32
	v_lshlrev_b32_e32 v226, 16, v226
	v_fmac_f32_e32 v68, v178, v12
	v_mul_f32_e32 v68, v68, v226
	v_cvt_pk_bf16_f32 v68, v68, s0
	ds_write_b16 v163, v68 offset:6208
	v_fma_f32 v69, v37, v179, v33
	v_lshlrev_b32_e32 v227, 16, v227
	v_fmac_f32_e32 v69, v178, v13
	v_mul_f32_e32 v69, v69, v227
	v_cvt_pk_bf16_f32 v69, v69, s0
	ds_write_b16 v163, v69 offset:6464
	v_fma_f32 v70, v38, v179, v34
	v_lshlrev_b32_e32 v228, 16, v228
	v_fmac_f32_e32 v70, v178, v14
	v_mul_f32_e32 v70, v70, v228
	v_cvt_pk_bf16_f32 v70, v70, s0
	ds_write_b16 v163, v70 offset:6720
	v_fma_f32 v71, v39, v179, v35
	v_lshlrev_b32_e32 v229, 16, v229
	v_fmac_f32_e32 v71, v178, v15
	v_mul_f32_e32 v71, v71, v229
	v_cvt_pk_bf16_f32 v71, v71, s0
	ds_write_b16 v163, v71 offset:6976
	s_add_i32 s44, s44, s30
	s_add_i32 s45, s45, s52
	s_waitcnt lgkmcnt(0)
	s_barrier
	ds_read_b128 v[0:3], v162
	ds_read_b128 v[4:7], v162 offset:8192
	ds_read_b128 v[8:11], v162 offset:16384
	ds_read_b128 v[12:15], v162 offset:24576
	s_cmpk_gt_i32 s44, 0xbff
	s_waitcnt lgkmcnt(0)
	global_store_dwordx4 v[138:139], v[0:3], off
	global_store_dwordx4 v[140:141], v[4:7], off
	global_store_dwordx4 v[142:143], v[8:11], off
	global_store_dwordx4 v[144:145], v[12:15], off
	s_barrier
	s_cbranch_scc0 .LBB0_114
